# k22 plus: static s_setprio 1 for waves 4-7 during the token-mixer phase (attention and S5 units), reset at its end
# baseline (speedup 1.0000x reference)
; #define LAS __attribute__((address_space(3)))
; __device__ __forceinline__ void ssm_unit(unsigned char* ws, LAS unsigned char* lds, int b, int g0, int lane, int wave) {
;     const int r16 = lane & 15, q4 = lane >> 4, sub = wave >> 2, w4 = wave & 3, g = g0 + sub;
;     LAS float* DL = (LAS float*)(lds + sub * SSM_SUB); LAS bf16* S0 = (LAS bf16*)(lds + sub * SSM_SUB + 64 * SSM_DROW * 4);
;     const bf16* Ms = (const bf16*)(ws + WS_SSMMAT) + (size_t)g * 3 * 16384; const bf16* Mi = Ms + 16384; const bf16* Mo = Mi + 16384;
;     bf16x8 aS[2][4], aI[2][4];
; #pragma unroll
;     for (int ct = 0; ct < 2; ++ct)
; #pragma unroll
;         for (int ks = 0; ks < 4; ++ks) { const int o = (32 * w4 + 16 * ct + r16) * 128 + 32 * ks + 8 * q4; aS[ct][ks] = *(const bf16x8*)(Ms + o); aI[ct][ks] = *(const bf16x8*)(Mi + o); }
;     const bf16* ug = (const bf16*)(ws + WS_UG) + (size_t)(b * 64 + g) * 4096 * 16;
;     bf16* zb = (bf16*)(ws + WS_Z) + (size_t)b * 4096 * 1024 + g * 16;
;     const float* l8 = (const float*)(ws + WS_LAM8) + (g * 64 + lane) * 2; const float l8r = l8[0], l8i = l8[1];
; __global__ void __launch_bounds__(NTHREADS, 2) mk_fwd(Args args) {
;     ...
;     { FRESH_IDS
;         for (int itt = bx; itt < (256 + 2048) * P4_REP; itt += G) { const int it = itt % (256 + 2048);
;             unsigned o2_ = ~0u; asm volatile("" : "+s"(o2_)); const int lane2 = (int)__builtin_amdgcn_mbcnt_hi(o2_, __builtin_amdgcn_mbcnt_lo(o2_, 0u)), tid2 = wave * 64 + lane2;
;             if (it < 256) ssm_unit(ws, lds, it >> 5, 2 * (it & 31), lane2, wave);
;             else { const int a = it - 256; attn_unit(ws, lds, a >> 8, (a >> 5) & 7, a & 31, tid2, lane2, wave, itt >= (256 + 2048) * (P4_REP - 1)); }
.LBB0_495:
	s_or_b64 exec, exec, s[8:9]
	s_mov_b32 s8, -1
	s_cmpk_gt_i32 s2, 0x8ff
	s_waitcnt lgkmcnt(0)
	s_barrier
	s_cbranch_scc1 .LBB0_521
	s_cmpk_gt_u32 s33, 0xff
	s_cbranch_scc0 .Lp4_noprio
	s_setprio 1
.Lp4_noprio:
	v_readlane_b32 s8, v255, 3
	s_lshl_b32 s18, s8, 4
	s_add_u32 s20, s68, 0x20000000
	s_addc_u32 s21, s69, 0
	s_add_u32 s22, s68, 0x24000000
	s_addc_u32 s23, s69, 0
	s_lshl_b32 s8, s8, 2
	s_add_i32 s46, s8, 0
	s_add_i32 s46, s46, 0x1f000
	s_add_u32 s47, s68, 0x60000
	s_mul_i32 s8, s19, 0xc800
	s_addc_u32 s64, s69, 0
	s_add_i32 s65, s8, 0
	s_add_u32 s66, s68, 0x200000
	s_addc_u32 s67, s69, 0
	s_add_u32 s42, s68, 0x100000
	s_addc_u32 s43, s69, 0
	s_add_u32 s74, s68, 0x2c000000
	s_addc_u32 s75, s69, 0
	s_lshl_b32 s8, s86, 7
	s_add_i32 s76, s65, s8
	s_cmp_eq_u32 s86, 0
	v_mbcnt_hi_u32_b32 v209, -1, v254
	s_mov_b32 s41, 0
	s_cselect_b64 s[50:51], -1, 0
	s_lshl_b32 s77, s86, 1
	s_add_i32 s78, s65, 0x8400
	v_mov_b32_e32 v193, 0
	s_mov_b64 s[52:53], 0x10000
	v_mov_b32_e32 v208, 0xf149f2ca
	v_and_b32_e32 v210, 64, v209
	s_mov_b32 s79, s2
	s_branch .LBB0_499

; __device__ __forceinline__ unsigned xb_ld(unsigned* p)              { return __hip_atomic_load(p, __ATOMIC_RELAXED, __HIP_MEMORY_SCOPE_AGENT); }
; __device__ __forceinline__ void xcd_barrier_complete(unsigned* bar, unsigned x, unsigned& nloc, unsigned& nx) {
;     const unsigned G = gridDim.x * gridDim.y * gridDim.z;
;     unsigned sum, cnt, mine, sp = 0u;
;     for (;;) {
;         sum = 0u; cnt = 0u; mine = 0u;
; #pragma unroll
;         for (unsigned j = 0; j < 16; ++j) { const unsigned c = xb_ld(&bar[XB_XCNT(j)]); sum += c; cnt += (c > 0u) ? 1u : 0u; mine = (j == x) ? c : mine; }
; __device__ __forceinline__ void xcd_barrier(const XcdBarrier& b) {
;     asm volatile("s_waitcnt vmcnt(0)" ::: "memory");
;     __syncthreads();
;     if (threadIdx.x == 0) {
;         unsigned* bar = b.bar;
;         __builtin_amdgcn_s_waitcnt(0);
;         unsigned nloc = b.st[0], nx = b.st[1];
;         if (nloc == 0u) { xcd_barrier_complete(bar, b.x, nloc, nx); b.st[0] = nloc; b.st[1] = nx; }
.LBB0_521:
	s_setprio 0
	s_waitcnt vmcnt(0)
	s_barrier
	s_and_saveexec_b64 s[8:9], s[0:1]
	s_cbranch_execz .LBB0_573
	s_add_i32 s10, 0, 0x23000
	v_mov_b32_e32 v0, s10
	s_waitcnt vmcnt(0) expcnt(0) lgkmcnt(0)
	ds_read_b32 v2, v0
	s_add_i32 s10, 0, 0x23004
	v_mov_b32_e32 v0, s10
	ds_read_b32 v0, v0
	s_waitcnt lgkmcnt(1)
	v_cmp_ne_u32_e32 vcc, 0, v2
	s_cbranch_vccnz .LBB0_537
	v_readlane_b32 s10, v255, 0
	s_mul_i32 s18, s71, s10
	s_add_u32 s10, s68, 0xf0200
	s_addc_u32 s11, s69, 0
	s_add_u32 s12, s68, 0xf0400
	s_addc_u32 s13, s69, 0
	s_add_u32 s14, s68, 0xf0500
	s_addc_u32 s15, s69, 0
	s_add_u32 s40, s68, 0xf0600
	s_addc_u32 s41, s69, 0
	s_add_u32 s42, s68, 0xf0700
	s_addc_u32 s43, s69, 0
	s_add_u32 s48, s68, 0xf0800
	s_addc_u32 s49, s69, 0
	s_add_u32 s50, s68, 0xf0900
	s_addc_u32 s51, s69, 0
	s_add_u32 s52, s68, 0xf0a00
	s_addc_u32 s53, s69, 0
	s_add_u32 s54, s68, 0xf0b00
	s_addc_u32 s55, s69, 0
	s_add_u32 s56, s68, 0xf0c00
	s_addc_u32 s57, s69, 0
	s_add_u32 s58, s68, 0xf0d00
	s_addc_u32 s59, s69, 0
	s_add_u32 s60, s68, 0xf0e00
	s_addc_u32 s61, s69, 0
	s_add_u32 s62, s68, 0xf0f00
	s_addc_u32 s63, s69, 0
	s_add_u32 s64, s68, 0xf1000
	s_addc_u32 s65, s69, 0
	s_add_u32 s66, s68, 0xf1100
	s_addc_u32 s67, s69, 0
	s_add_u32 s74, s68, 0xf1200
	s_addc_u32 s75, s69, 0
	s_add_u32 s76, s68, 0xf1300
	s_mul_i32 s18, s18, s70
	s_addc_u32 s77, s69, 0
	s_mov_b32 s19, 1
	v_mov_b32_e32 v16, 0
	s_branch .LBB0_525
